# rowstat partials (bf16 dot2, permuted layout) with every hot K-loop padded to the same address mod 64 as the v18c build (placement-matched comparison)
# baseline (speedup 1.0000x reference)
.LBB0_1074:
	s_cmp_lt_u32 s2, 0x1000001
	s_mov_b64 s[28:29], 0
	s_cselect_b64 s[30:31], -1, 0
	s_and_b64 vcc, exec, s[30:31]
	s_cbranch_vccz .LBB0_1068
	s_branch .LBB0_1073
	s_nop 0
	s_nop 0

; #define PG8_STAGE(bufoff, gbase, voff) do { _Pragma("unroll") for (int _i = 0; _i < 2; ++_i) \
;         __builtin_amdgcn_global_load_lds((const unsigned*)((const char*)(gbase) + (voff)[_i]), (LAS unsigned*)(lds + (bufoff) + ldsw + _i * 8192), 16, 0, 0); } while (0)
; #define PG8_WAIT_V(n) asm volatile("s_waitcnt vmcnt(" #n ")" ::: "memory")
; #define PG8_BAR __builtin_amdgcn_s_barrier()
; template <class Epi, class Sched>
; __device__ __forceinline__ void gemm_phase(LAS unsigned char* lds, const Gemm g, const Sched& S, const Epi& E) {
;     ...
;     const char* cA = (const char*)g.A + (size_t)cur.pm * tstepA; const char* cB = (const char*)g.Bt + (size_t)cur.pn * tstepB;
;     S.a_ready(cur);
;     PG8_STAGE(PG8_SB(0, 0), cB, voffB); PG8_STAGE(PG8_SA(0, 0), cA, voffA); PG8_STAGE(PG8_SB(0, 1), cB + hstepB, voffB); PG8_STAGE(PG8_SA(0, 1), cA + hstepA, voffA);
;     if (wr == 1) PG8_BAR;
;     PG8_WAIT_V(4); PG8_BAR;
;     PG8_STAGE(PG8_SB(1, 0), cB + kstep, voffB); PG8_STAGE(PG8_SA(1, 0), cA + kstep, voffA); PG8_STAGE(PG8_SB(1, 1), cB + hstepB + kstep, voffB);
;     PG8_WAIT_V(6); PG8_BAR;
; __global__ void __launch_bounds__(NTHR, 2) mega(Args args) {
;     ...
;             pg8::Gemm g{RES, (const bf16_t*)(ws + WS_W_UP + layer * SZ_W_UP), M, FF2, D, D};
;             pg8::StaticOrder S; S.init(M, FF2, F.G, F.bid);
;             pg8::EpiFfnGate E{(bf16_t*)(ws + WS_ACT), F.in[I_F_CONVW] + (size_t)layer * 3 * FF, F.in[I_F_CONVB] + (size_t)layer * FF,
;                               (float*)(ws + WS_TAIL), (float*)(ws + WS_HEADG), (float*)(ws + WS_HEADU), F.lds + 131072, RSTD};
;             pg8::gemm_phase(F.lds, g, S, E);
.LBB0_1519:
	v_readlane_b32 s29, v255, 27
	s_mul_i32 s28, s29, 0x10800
	s_mul_hi_u32 s15, s29, 0x10800
	s_waitcnt lgkmcnt(0)
	s_add_u32 s36, s40, s28
	s_addc_u32 s37, s41, s15
	s_mul_i32 s28, s29, 0x5800
	v_readlane_b32 s58, v254, 23
	s_mul_hi_u32 s15, s29, 0x5800
	s_add_u32 s42, s42, s28
	v_mov_b32_e32 v181, v3
	v_readlane_b32 s59, v254, 24
	s_addc_u32 s43, s43, s15
	s_and_b32 s40, s14, 3
	s_add_i32 m0, s20, 0x18000
	v_lshl_add_u64 v[4:5], v[4:5], 0, s[8:9]
	v_lshl_add_u64 v[14:15], s[58:59], 0, v[180:181]
	v_mov_b32_e32 v177, v3
	s_lshl_b32 s28, s5, 6
	s_lshl_b32 s35, s5, 13
	s_lshl_b32 s29, s40, 5
	s_lshl_b32 s38, s40, 12
	s_waitcnt vmcnt(2)
	s_barrier
	global_load_lds_dwordx4 v[4:5], off
	v_lshl_add_u64 v[4:5], v[6:7], 0, s[8:9]
	s_add_i32 m0, s20, 0x1a000
	s_add_i32 s30, s20, 0x8000
	s_add_i32 s31, s20, 0xa000
	v_lshl_add_u64 v[16:17], s[58:59], 0, v[176:177]
	global_load_lds_dwordx4 v[4:5], off
	v_lshl_add_u64 v[4:5], v[14:15], 0, s[8:9]
	s_mov_b32 m0, s30
	s_add_u32 s14, s6, 0x80080
	global_load_lds_dwordx4 v[4:5], off
	v_lshl_add_u64 v[4:5], v[16:17], 0, s[8:9]
	s_mov_b32 m0, s31
	s_addc_u32 s15, s7, 0
	global_load_lds_dwordx4 v[4:5], off
	s_add_i32 m0, s20, 0x1c000
	v_lshl_add_u64 v[4:5], s[14:15], 0, v[178:179]
	global_load_lds_dwordx4 v[4:5], off
	v_lshl_add_u64 v[4:5], s[14:15], 0, v[174:175]
	s_add_i32 m0, s20, 0x1e000
	s_movk_i32 s14, 0x3c0
	global_load_lds_dwordx4 v[4:5], off
	v_and_b32_e32 v4, 48, v1
	v_lshlrev_b32_e32 v5, 6, v1
	v_lshlrev_b32_e32 v1, 2, v1
	v_and_or_b32 v4, v5, s14, v4
	v_and_b32_e32 v1, 32, v1
	s_and_b32 s14, s4, 0xffffff00
	v_bitop3_b32 v5, v4, s35, v1 bitop3:0xde
	s_add_i32 s35, s14, 0
	s_lshl_b32 s14, s5, 5
	s_lshl_b32 s15, s40, 3
	v_bitop3_b32 v1, v4, s38, v1 bitop3:0xde
	s_or_b32 s38, s15, s14
	s_add_i32 s35, s35, 0x21000
	s_add_i32 s39, s38, 64
	s_cmpk_gt_u32 s4, 0xff
	s_cselect_b64 s[44:45], -1, 0
	s_lshl_b32 s40, s40, 8
	s_cmp_lg_u32 s5, 1
	s_cselect_b64 s[14:15], -1, 0
	v_cndmask_b32_e64 v4, 0, 1, s[14:15]
	s_and_b64 s[14:15], s[14:15], exec
	s_cselect_b32 s14, 0, 2
	v_readfirstlane_b32 s15, v4
	s_cselect_b32 s5, 0x400, 0
	s_or_b32 s14, s14, s15
	s_lshl_b32 s14, s14, 10
	v_lshlrev_b32_e32 v4, 15, v11
	s_cmpk_lt_u32 s4, 0x100
	v_and_b32_e32 v4, 0xffff0000, v4
	s_cselect_b64 s[46:47], -1, 0
	s_add_u32 s48, s36, 0x5800
	v_lshl_add_u32 v4, v10, 12, v4
	v_and_b32_e32 v6, 1, v11
	s_addc_u32 s49, s37, 0
	v_lshl_or_b32 v4, v6, 6, v4
	s_add_u32 s50, s36, 0xb000
	v_lshl_add_u32 v182, v12, 1, v4
	v_lshlrev_b32_e32 v4, 15, v2
	s_addc_u32 s51, s37, 0
	s_add_i32 s62, 0, 0x20000
	v_and_b32_e32 v4, 0xffff0000, v4
	s_waitcnt vmcnt(6)
	s_add_i32 s63, s62, s5
	v_lshl_add_u32 v4, v8, 12, v4
	v_and_b32_e32 v2, 1, v2
	v_readlane_b32 s4, v254, 21
	s_add_i32 s64, s62, s14
	v_lshl_or_b32 v2, v2, 6, v4
	v_readlane_b32 s5, v254, 22
	s_mov_b32 s66, 0
	s_add_i32 s63, s63, s40
	s_add_i32 s64, s64, s40
	v_mov_b32_e32 v183, v3
	v_lshl_add_u32 v184, v9, 1, v2
	v_mov_b32_e32 v185, v3
	v_add_u32_e32 v207, 0, v5
	v_readlane_b32 s53, v254, 18
	s_mov_b32 s52, s4
	s_mov_b64 s[4:5], s[58:59]
	s_barrier
	s_branch .LBB0_1521
	s_nop 0
